# v23 + GEMM1 plain epilogue scalar q-scale select (no per-element cndmask) + MLP-up epilogue lane^16/lane^32 sums via v_permlane16/32_swap instead of ds_bpermute
# speedup vs baseline: 1.0068x; 1.0068x over previous
; __device__ __forceinline__ unsigned cvt_pk_bf16(float lo, float hi) { const f32x2c_t v = {lo, hi}; const bf16x2c_t b = __builtin_convertvector(v, bf16x2c_t); return __builtin_bit_cast(unsigned, b); }
;     __device__ __forceinline__ void operator()(const f32x4 (&acc)[2][2][4][2], const Unit& u, int wr, int wc, int fr, int fq) const {
;     ...
;             for (int m = 0; m < 4; ++m) { const size_t row = (size_t)(row0 + ai * HALF + m * 16);
;                 const f32x4* sp = (const f32x4*)(SS + row * 32) + 2 * fq; float s;
;                 { const f32x4 t0 = sp[0], t1 = sp[1]; s = ((t0[0] + t0[1]) + (t0[2] + t0[3])) + ((t1[0] + t1[1]) + (t1[2] + t1[3])); }
;                 s += __shfl_xor(s, 16); s += __shfl_xor(s, 32);
;                 const float rstd = 1.0f / sqrtf(s * (1.0f / DM) + NORM_EPS);
; #pragma unroll
;                 for (int bj = 0; bj < 2; ++bj) { f32x4 v0 = acc[ai][bj][m][0] * rstd, v1 = acc[ai][bj][m][1] * rstd;
; #pragma unroll
;                     for (int e = 0; e < 4; ++e) { const float a = fmaxf(v0[e], 0.f), b = fmaxf(v1[e], 0.f); v0[e] = a * a; v1[e] = b * b; }
;                     u32x4 w; w.x = cvt_pk_bf16(v0[0], v0[1]); w.y = cvt_pk_bf16(v0[2], v0[3]); w.z = cvt_pk_bf16(v1[0], v1[1]); w.w = cvt_pk_bf16(v1[2], v1[3]);
;                     *(u32x4*)(H + row * DFF + col0 + bj * HALF) = w; } }
.LBB0_79:
	v_xor_b32_e32 v159, 16, v192
	v_add_u32_e32 v163, 64, v193
	v_cmp_lt_i32_e32 vcc, v159, v163
	v_lshl_add_u32 v158, s34, 8, v1
	v_lshl_or_b32 v172, s28, 8, v160
	v_cndmask_b32_e32 v159, v192, v159, vcc
	v_lshlrev_b32_e32 v162, 2, v159
	v_xor_b32_e32 v159, 32, v192
	v_cmp_lt_i32_e32 vcc, v159, v163
	v_ashrrev_i32_e32 v173, 31, v172
	s_nop 0
	v_cndmask_b32_e32 v159, v192, v159, vcc
	v_lshlrev_b32_e32 v163, 2, v159
	v_ashrrev_i32_e32 v159, 31, v158
	v_lshlrev_b64 v[164:165], 7, v[158:159]
	v_lshl_add_u64 v[168:169], v[152:153], 0, v[164:165]
	global_load_dwordx4 v[164:167], v[168:169], off
	s_nop 0
	global_load_dwordx4 v[168:171], v[168:169], off offset:16
	s_waitcnt vmcnt(0)
	v_mov_b32_e32 v174, v164
	v_mov_b32_e32 v175, v168
	v_mov_b32_e32 v168, v165
	v_pk_add_f32 v[164:165], v[174:175], v[168:169]
	v_mov_b32_e32 v168, v166
	v_mov_b32_e32 v169, v170
	v_mov_b32_e32 v170, v167
	v_pk_add_f32 v[166:167], v[168:169], v[170:171]
	s_nop 0
	v_pk_add_f32 v[164:165], v[164:165], v[166:167]
	s_nop 0
	v_add_f32_e32 v164, v164, v165
	v_mov_b32_e32 v165, v164
	s_nop 1
	v_permlane16_swap_b32_e32 v165, v164
	s_waitcnt lgkmcnt(0)
	v_add_f32_e32 v164, v164, v165
	v_mov_b32_e32 v165, v164
	s_nop 1
	v_permlane32_swap_b32_e32 v165, v164
	s_waitcnt lgkmcnt(0)
	v_add_f32_e32 v164, v164, v165
	v_fmamk_f32 v164, v164, 0x3a000000, v190
	v_cmp_gt_f32_e32 vcc, s72, v164
	v_mul_f32_e32 v165, 0x4f800000, v164
	s_nop 0
	v_cndmask_b32_e32 v164, v164, v165, vcc
	v_sqrt_f32_e32 v165, v164
	s_nop 0
	v_add_u32_e32 v166, -1, v165
	v_fma_f32 v167, -v166, v165, v164
	v_cmp_ge_f32_e64 s[0:1], 0, v167
	v_add_u32_e32 v167, 1, v165
	s_nop 0
	v_cndmask_b32_e64 v166, v165, v166, s[0:1]
	v_fma_f32 v165, -v167, v165, v164
	v_cmp_lt_f32_e64 s[0:1], 0, v165
	s_nop 1
	v_cndmask_b32_e64 v165, v166, v167, s[0:1]
	v_mul_f32_e32 v166, 0x37800000, v165
	v_cndmask_b32_e32 v165, v165, v166, vcc
	v_cmp_class_f32_e32 vcc, v164, v191
	s_nop 1
	v_cndmask_b32_e32 v164, v165, v164, vcc
	v_div_scale_f32 v165, s[0:1], v164, v164, 1.0
	v_rcp_f32_e32 v166, v165
	s_nop 0
	v_fma_f32 v167, -v165, v166, 1.0
	v_fmac_f32_e32 v166, v167, v166
	v_div_scale_f32 v167, vcc, 1.0, v164, 1.0
	v_mul_f32_e32 v168, v167, v166
	v_fma_f32 v169, -v165, v168, v167
	v_fmac_f32_e32 v168, v169, v166
	v_fma_f32 v165, -v165, v168, v167
	v_div_fmas_f32 v165, v165, v166, v168
	v_div_fixup_f32 v164, v165, v164, 1.0
	v_pk_mul_f32 v[128:129], v[128:129], v[164:165] op_sel_hi:[1,0]
	v_pk_mul_f32 v[126:127], v[126:127], v[164:165] op_sel_hi:[1,0]
	v_pk_mul_f32 v[122:123], v[122:123], v[164:165] op_sel_hi:[1,0]
	v_pk_mul_f32 v[124:125], v[124:125], v[164:165] op_sel_hi:[1,0]
	v_max_f32_e32 v126, 0, v126
	v_max_f32_e32 v122, 0, v122
	v_max_f32_e32 v127, 0, v127
	v_max_f32_e32 v123, 0, v123
	v_max_f32_e32 v128, 0, v128
	v_max_f32_e32 v129, 0, v129
	v_lshlrev_b64 v[166:167], 14, v[158:159]
	v_pk_mul_f32 v[126:127], v[126:127], v[126:127]
	v_pk_mul_f32 v[122:123], v[122:123], v[122:123]
	v_max_f32_e32 v124, 0, v124
	v_max_f32_e32 v125, 0, v125
	v_pk_mul_f32 v[128:129], v[128:129], v[128:129]
	v_pk_mul_f32 v[168:169], v[124:125], v[124:125]
	v_cvt_pk_bf16_f32 v124, v126, v127
	v_cvt_pk_bf16_f32 v125, v128, v129
	v_cvt_pk_bf16_f32 v126, v122, v123
	v_lshl_add_u64 v[128:129], s[92:93], 0, v[166:167]
	v_lshlrev_b64 v[122:123], 1, v[172:173]
	v_pk_mul_f32 v[114:115], v[114:115], v[164:165] op_sel_hi:[1,0]
	v_cvt_pk_bf16_f32 v127, v168, v169
	v_lshl_add_u64 v[128:129], v[128:129], 0, v[122:123]
	v_pk_mul_f32 v[120:121], v[120:121], v[164:165] op_sel_hi:[1,0]
	v_pk_mul_f32 v[118:119], v[118:119], v[164:165] op_sel_hi:[1,0]
	v_pk_mul_f32 v[116:117], v[116:117], v[164:165] op_sel_hi:[1,0]
	v_max_f32_e32 v114, 0, v114
	v_max_f32_e32 v115, 0, v115
	global_store_dwordx4 v[128:129], v[124:127], off
	v_max_f32_e32 v118, 0, v118
	v_max_f32_e32 v119, 0, v119
	v_pk_mul_f32 v[124:125], v[114:115], v[114:115]
	v_max_f32_e32 v114, 0, v120
	v_max_f32_e32 v116, 0, v116
	v_max_f32_e32 v115, 0, v121
	v_max_f32_e32 v117, 0, v117
	v_pk_mul_f32 v[118:119], v[118:119], v[118:119]
	v_pk_mul_f32 v[120:121], v[114:115], v[114:115]
	v_pk_mul_f32 v[126:127], v[116:117], v[116:117]
	v_cvt_pk_bf16_f32 v114, v118, v119
	v_cvt_pk_bf16_f32 v115, v120, v121
	v_cvt_pk_bf16_f32 v116, v124, v125
	v_cvt_pk_bf16_f32 v117, v126, v127
	global_store_dwordx4 v[128:129], v[114:117], off offset:256
	s_nop 1
	v_or_b32_e32 v114, 16, v158
	v_ashrrev_i32_e32 v115, 31, v114
	v_lshlrev_b64 v[116:117], 7, v[114:115]
	v_lshl_add_u64 v[120:121], v[152:153], 0, v[116:117]
	global_load_dwordx4 v[116:119], v[120:121], off
	global_load_dwordx4 v[124:127], v[120:121], off offset:16
	v_lshlrev_b64 v[114:115], 14, v[114:115]
	s_waitcnt vmcnt(1)
	v_mov_b32_e32 v120, v116
	s_waitcnt vmcnt(0)
	v_mov_b32_e32 v121, v124
	v_mov_b32_e32 v124, v117
	v_pk_add_f32 v[116:117], v[120:121], v[124:125]
	v_mov_b32_e32 v120, v118
	v_mov_b32_e32 v121, v126
	v_mov_b32_e32 v126, v119
	v_pk_add_f32 v[118:119], v[120:121], v[126:127]
	s_nop 0
	v_pk_add_f32 v[116:117], v[116:117], v[118:119]
	s_nop 0
	v_add_f32_e32 v116, v116, v117
	v_mov_b32_e32 v117, v116
	s_nop 1
	v_permlane16_swap_b32_e32 v117, v116
	s_waitcnt lgkmcnt(0)
	v_add_f32_e32 v116, v116, v117
	v_mov_b32_e32 v117, v116
	s_nop 1
	v_permlane32_swap_b32_e32 v117, v116
	s_waitcnt lgkmcnt(0)
; __device__ __forceinline__ unsigned cvt_pk_bf16(float lo, float hi) { const f32x2c_t v = {lo, hi}; const bf16x2c_t b = __builtin_convertvector(v, bf16x2c_t); return __builtin_bit_cast(unsigned, b); }
;     __device__ __forceinline__ void operator()(const f32x4 (&acc)[2][2][4][2], const Unit& u, int wr, int wc, int fr, int fq) const {
;     ...
;             for (int m = 0; m < 4; ++m) { const size_t row = (size_t)(row0 + ai * HALF + m * 16);
;                 const f32x4* sp = (const f32x4*)(SS + row * 32) + 2 * fq; float s;
;                 { const f32x4 t0 = sp[0], t1 = sp[1]; s = ((t0[0] + t0[1]) + (t0[2] + t0[3])) + ((t1[0] + t1[1]) + (t1[2] + t1[3])); }
;                 s += __shfl_xor(s, 16); s += __shfl_xor(s, 32);
;                 const float rstd = 1.0f / sqrtf(s * (1.0f / DM) + NORM_EPS);
; #pragma unroll
;                 for (int bj = 0; bj < 2; ++bj) { f32x4 v0 = acc[ai][bj][m][0] * rstd, v1 = acc[ai][bj][m][1] * rstd;
; #pragma unroll
;                     for (int e = 0; e < 4; ++e) { const float a = fmaxf(v0[e], 0.f), b = fmaxf(v1[e], 0.f); v0[e] = a * a; v1[e] = b * b; }
;                     u32x4 w; w.x = cvt_pk_bf16(v0[0], v0[1]); w.y = cvt_pk_bf16(v0[2], v0[3]); w.z = cvt_pk_bf16(v1[0], v1[1]); w.w = cvt_pk_bf16(v1[2], v1[3]);
;                     *(u32x4*)(H + row * DFF + col0 + bj * HALF) = w; } }
	v_add_f32_e32 v116, v116, v117
	v_fmamk_f32 v116, v116, 0x3a000000, v190
	v_cmp_gt_f32_e32 vcc, s72, v116
	v_mul_f32_e32 v117, 0x4f800000, v116
	s_nop 0
	v_cndmask_b32_e32 v116, v116, v117, vcc
	v_sqrt_f32_e32 v117, v116
	s_nop 0
	v_add_u32_e32 v118, -1, v117
	v_fma_f32 v119, -v118, v117, v116
	v_cmp_ge_f32_e64 s[0:1], 0, v119
	v_add_u32_e32 v119, 1, v117
	s_nop 0
	v_cndmask_b32_e64 v118, v117, v118, s[0:1]
	v_fma_f32 v117, -v119, v117, v116
	v_cmp_lt_f32_e64 s[0:1], 0, v117
	s_nop 1
	v_cndmask_b32_e64 v117, v118, v119, s[0:1]
	v_mul_f32_e32 v118, 0x37800000, v117
	v_cndmask_b32_e32 v117, v117, v118, vcc
	v_cmp_class_f32_e32 vcc, v116, v191
	s_nop 1
	v_cndmask_b32_e32 v116, v117, v116, vcc
	v_div_scale_f32 v117, s[0:1], v116, v116, 1.0
	v_rcp_f32_e32 v118, v117
	s_nop 0
	v_fma_f32 v119, -v117, v118, 1.0
	v_fmac_f32_e32 v118, v119, v118
	v_div_scale_f32 v119, vcc, 1.0, v116, 1.0
	v_mul_f32_e32 v120, v119, v118
	v_fma_f32 v121, -v117, v120, v119
	v_fmac_f32_e32 v120, v121, v118
	v_fma_f32 v117, -v117, v120, v119
	v_div_fmas_f32 v117, v117, v118, v120
	v_div_fixup_f32 v116, v117, v116, 1.0
	v_pk_mul_f32 v[110:111], v[110:111], v[116:117] op_sel_hi:[1,0]
	v_pk_mul_f32 v[106:107], v[106:107], v[116:117] op_sel_hi:[1,0]
	v_pk_mul_f32 v[112:113], v[112:113], v[116:117] op_sel_hi:[1,0]
	v_pk_mul_f32 v[108:109], v[108:109], v[116:117] op_sel_hi:[1,0]
	v_max_f32_e32 v110, 0, v110
	v_max_f32_e32 v106, 0, v106
	v_max_f32_e32 v111, 0, v111
	v_max_f32_e32 v107, 0, v107
	v_pk_mul_f32 v[110:111], v[110:111], v[110:111]
	v_pk_mul_f32 v[118:119], v[106:107], v[106:107]
	v_max_f32_e32 v106, 0, v112
	v_max_f32_e32 v108, 0, v108
	v_max_f32_e32 v107, 0, v113
	v_max_f32_e32 v109, 0, v109
	v_pk_mul_f32 v[112:113], v[106:107], v[106:107]
	v_pk_mul_f32 v[120:121], v[108:109], v[108:109]
	v_cvt_pk_bf16_f32 v106, v110, v111
	v_lshl_add_u64 v[110:111], s[92:93], 0, v[114:115]
	v_pk_mul_f32 v[98:99], v[98:99], v[116:117] op_sel_hi:[1,0]
	v_cvt_pk_bf16_f32 v107, v112, v113
	v_cvt_pk_bf16_f32 v108, v118, v119
	v_cvt_pk_bf16_f32 v109, v120, v121
	v_lshl_add_u64 v[110:111], v[110:111], 0, v[122:123]
	v_pk_mul_f32 v[104:105], v[104:105], v[116:117] op_sel_hi:[1,0]
	v_pk_mul_f32 v[102:103], v[102:103], v[116:117] op_sel_hi:[1,0]
	v_pk_mul_f32 v[100:101], v[100:101], v[116:117] op_sel_hi:[1,0]
	v_max_f32_e32 v98, 0, v98
	v_max_f32_e32 v99, 0, v99
	global_store_dwordx4 v[110:111], v[106:109], off
	v_max_f32_e32 v102, 0, v102
	v_max_f32_e32 v103, 0, v103
	v_pk_mul_f32 v[106:107], v[98:99], v[98:99]
	v_max_f32_e32 v98, 0, v104
	v_max_f32_e32 v100, 0, v100
	v_max_f32_e32 v99, 0, v105
	v_max_f32_e32 v101, 0, v101
	v_pk_mul_f32 v[102:103], v[102:103], v[102:103]
	v_pk_mul_f32 v[104:105], v[98:99], v[98:99]
	v_pk_mul_f32 v[108:109], v[100:101], v[100:101]
	v_cvt_pk_bf16_f32 v98, v102, v103
	v_cvt_pk_bf16_f32 v99, v104, v105
	v_cvt_pk_bf16_f32 v100, v106, v107
	v_cvt_pk_bf16_f32 v101, v108, v109
	global_store_dwordx4 v[110:111], v[98:101], off offset:256
	s_nop 1
	v_or_b32_e32 v98, 32, v158
	v_ashrrev_i32_e32 v99, 31, v98
	v_lshlrev_b64 v[100:101], 7, v[98:99]
	v_lshl_add_u64 v[100:101], v[152:153], 0, v[100:101]
	global_load_dwordx4 v[102:105], v[100:101], off
	global_load_dwordx4 v[106:109], v[100:101], off offset:16
	v_lshlrev_b64 v[98:99], 14, v[98:99]
	s_waitcnt vmcnt(1)
	v_mov_b32_e32 v100, v102
	s_waitcnt vmcnt(0)
	v_mov_b32_e32 v101, v106
	v_mov_b32_e32 v106, v103
	v_mov_b32_e32 v102, v104
	v_mov_b32_e32 v103, v108
	v_mov_b32_e32 v108, v105
	v_pk_add_f32 v[100:101], v[100:101], v[106:107]
	v_pk_add_f32 v[102:103], v[102:103], v[108:109]
	s_nop 0
	v_pk_add_f32 v[100:101], v[100:101], v[102:103]
	s_nop 0
	v_add_f32_e32 v100, v100, v101
	v_mov_b32_e32 v101, v100
	s_nop 1
	v_permlane16_swap_b32_e32 v101, v100
	s_waitcnt lgkmcnt(0)
	v_add_f32_e32 v100, v100, v101
	v_mov_b32_e32 v101, v100
	s_nop 1
	v_permlane32_swap_b32_e32 v101, v100
	s_waitcnt lgkmcnt(0)
	v_add_f32_e32 v100, v100, v101
	v_fmamk_f32 v100, v100, 0x3a000000, v190
	v_cmp_gt_f32_e32 vcc, s72, v100
	v_mul_f32_e32 v101, 0x4f800000, v100
	s_nop 0
	v_cndmask_b32_e32 v100, v100, v101, vcc
	v_sqrt_f32_e32 v101, v100
	s_nop 0
	v_add_u32_e32 v102, -1, v101
	v_fma_f32 v103, -v102, v101, v100
	v_cmp_ge_f32_e64 s[0:1], 0, v103
	v_add_u32_e32 v103, 1, v101
	s_nop 0
	v_cndmask_b32_e64 v102, v101, v102, s[0:1]
	v_fma_f32 v101, -v103, v101, v100
	v_cmp_lt_f32_e64 s[0:1], 0, v101
	s_nop 1
	v_cndmask_b32_e64 v101, v102, v103, s[0:1]
	v_mul_f32_e32 v102, 0x37800000, v101
	v_cndmask_b32_e32 v101, v101, v102, vcc
	v_cmp_class_f32_e32 vcc, v100, v191
	s_nop 1
	v_cndmask_b32_e32 v100, v101, v100, vcc
	v_div_scale_f32 v101, s[0:1], v100, v100, 1.0
	v_rcp_f32_e32 v102, v101
	s_nop 0
	v_fma_f32 v103, -v101, v102, 1.0
	v_fmac_f32_e32 v102, v103, v102
	v_div_scale_f32 v103, vcc, 1.0, v100, 1.0
	v_mul_f32_e32 v104, v103, v102
	v_fma_f32 v105, -v101, v104, v103
	v_fmac_f32_e32 v104, v105, v102
	v_fma_f32 v101, -v101, v104, v103
	v_div_fmas_f32 v101, v101, v102, v104
	v_div_fixup_f32 v100, v101, v100, 1.0
	v_pk_mul_f32 v[94:95], v[94:95], v[100:101] op_sel_hi:[1,0]
	v_pk_mul_f32 v[90:91], v[90:91], v[100:101] op_sel_hi:[1,0]
	v_pk_mul_f32 v[96:97], v[96:97], v[100:101] op_sel_hi:[1,0]
	v_pk_mul_f32 v[92:93], v[92:93], v[100:101] op_sel_hi:[1,0]
	v_max_f32_e32 v94, 0, v94
	v_max_f32_e32 v90, 0, v90
	v_max_f32_e32 v95, 0, v95
	v_max_f32_e32 v91, 0, v91
	v_pk_mul_f32 v[94:95], v[94:95], v[94:95]
	v_pk_mul_f32 v[102:103], v[90:91], v[90:91]
	v_max_f32_e32 v90, 0, v96
	v_max_f32_e32 v92, 0, v92
	v_max_f32_e32 v91, 0, v97
	v_max_f32_e32 v93, 0, v93
	v_pk_mul_f32 v[96:97], v[90:91], v[90:91]
	v_pk_mul_f32 v[104:105], v[92:93], v[92:93]
	v_cvt_pk_bf16_f32 v90, v94, v95
	v_lshl_add_u64 v[94:95], s[92:93], 0, v[98:99]
	v_pk_mul_f32 v[82:83], v[82:83], v[100:101] op_sel_hi:[1,0]
	v_cvt_pk_bf16_f32 v91, v96, v97
	v_cvt_pk_bf16_f32 v92, v102, v103
	v_cvt_pk_bf16_f32 v93, v104, v105
	v_lshl_add_u64 v[94:95], v[94:95], 0, v[122:123]
	v_pk_mul_f32 v[88:89], v[88:89], v[100:101] op_sel_hi:[1,0]
	v_pk_mul_f32 v[86:87], v[86:87], v[100:101] op_sel_hi:[1,0]
	v_pk_mul_f32 v[84:85], v[84:85], v[100:101] op_sel_hi:[1,0]
	v_max_f32_e32 v82, 0, v82
	v_max_f32_e32 v83, 0, v83
	global_store_dwordx4 v[94:95], v[90:93], off
	v_max_f32_e32 v86, 0, v86
	v_max_f32_e32 v87, 0, v87
	v_pk_mul_f32 v[90:91], v[82:83], v[82:83]
	v_max_f32_e32 v82, 0, v88
	v_max_f32_e32 v84, 0, v84
	v_max_f32_e32 v83, 0, v89
	v_max_f32_e32 v85, 0, v85
	v_pk_mul_f32 v[86:87], v[86:87], v[86:87]
	v_pk_mul_f32 v[88:89], v[82:83], v[82:83]
	v_pk_mul_f32 v[92:93], v[84:85], v[84:85]
	v_cvt_pk_bf16_f32 v82, v86, v87
	v_cvt_pk_bf16_f32 v83, v88, v89
	v_cvt_pk_bf16_f32 v84, v90, v91
	v_cvt_pk_bf16_f32 v85, v92, v93
	global_store_dwordx4 v[94:95], v[82:85], off offset:256
	s_nop 1
	v_or_b32_e32 v82, 48, v158
	v_ashrrev_i32_e32 v83, 31, v82
	v_lshlrev_b64 v[84:85], 7, v[82:83]
	v_lshl_add_u64 v[84:85], v[152:153], 0, v[84:85]
	global_load_dwordx4 v[86:89], v[84:85], off
	global_load_dwordx4 v[90:93], v[84:85], off offset:16
	v_lshlrev_b64 v[82:83], 14, v[82:83]
	s_waitcnt vmcnt(1)
; __device__ __forceinline__ unsigned cvt_pk_bf16(float lo, float hi) { const f32x2c_t v = {lo, hi}; const bf16x2c_t b = __builtin_convertvector(v, bf16x2c_t); return __builtin_bit_cast(unsigned, b); }
;     __device__ __forceinline__ void operator()(const f32x4 (&acc)[2][2][4][2], const Unit& u, int wr, int wc, int fr, int fq) const {
;     ...
;             for (int m = 0; m < 4; ++m) { const size_t row = (size_t)(row0 + ai * HALF + m * 16);
;                 const f32x4* sp = (const f32x4*)(SS + row * 32) + 2 * fq; float s;
;                 { const f32x4 t0 = sp[0], t1 = sp[1]; s = ((t0[0] + t0[1]) + (t0[2] + t0[3])) + ((t1[0] + t1[1]) + (t1[2] + t1[3])); }
;                 s += __shfl_xor(s, 16); s += __shfl_xor(s, 32);
;                 const float rstd = 1.0f / sqrtf(s * (1.0f / DM) + NORM_EPS);
; #pragma unroll
;                 for (int bj = 0; bj < 2; ++bj) { f32x4 v0 = acc[ai][bj][m][0] * rstd, v1 = acc[ai][bj][m][1] * rstd;
; #pragma unroll
;                     for (int e = 0; e < 4; ++e) { const float a = fmaxf(v0[e], 0.f), b = fmaxf(v1[e], 0.f); v0[e] = a * a; v1[e] = b * b; }
;                     u32x4 w; w.x = cvt_pk_bf16(v0[0], v0[1]); w.y = cvt_pk_bf16(v0[2], v0[3]); w.z = cvt_pk_bf16(v1[0], v1[1]); w.w = cvt_pk_bf16(v1[2], v1[3]);
;                     *(u32x4*)(H + row * DFF + col0 + bj * HALF) = w; } }
	v_mov_b32_e32 v84, v86
	s_waitcnt vmcnt(0)
	v_mov_b32_e32 v85, v90
	v_mov_b32_e32 v90, v87
	v_mov_b32_e32 v86, v88
	v_mov_b32_e32 v87, v92
	v_mov_b32_e32 v92, v89
	v_pk_add_f32 v[84:85], v[84:85], v[90:91]
	v_pk_add_f32 v[86:87], v[86:87], v[92:93]
	s_nop 0
	v_pk_add_f32 v[84:85], v[84:85], v[86:87]
	s_nop 0
	v_add_f32_e32 v84, v84, v85
	v_mov_b32_e32 v85, v84
	s_nop 1
	v_permlane16_swap_b32_e32 v85, v84
	s_waitcnt lgkmcnt(0)
	v_add_f32_e32 v84, v84, v85
	v_mov_b32_e32 v85, v84
	s_nop 1
	v_permlane32_swap_b32_e32 v85, v84
	s_waitcnt lgkmcnt(0)
	v_add_f32_e32 v84, v84, v85
	v_fmamk_f32 v84, v84, 0x3a000000, v190
	v_cmp_gt_f32_e32 vcc, s72, v84
	v_mul_f32_e32 v85, 0x4f800000, v84
	s_nop 0
	v_cndmask_b32_e32 v84, v84, v85, vcc
	v_sqrt_f32_e32 v85, v84
	s_nop 0
	v_add_u32_e32 v86, -1, v85
	v_fma_f32 v87, -v86, v85, v84
	v_cmp_ge_f32_e64 s[0:1], 0, v87
	v_add_u32_e32 v87, 1, v85
	s_nop 0
	v_cndmask_b32_e64 v86, v85, v86, s[0:1]
	v_fma_f32 v85, -v87, v85, v84
	v_cmp_lt_f32_e64 s[0:1], 0, v85
	s_nop 1
	v_cndmask_b32_e64 v85, v86, v87, s[0:1]
	v_mul_f32_e32 v86, 0x37800000, v85
	v_cndmask_b32_e32 v85, v85, v86, vcc
	v_cmp_class_f32_e32 vcc, v84, v191
	s_nop 1
	v_cndmask_b32_e32 v84, v85, v84, vcc
	v_div_scale_f32 v85, s[0:1], v84, v84, 1.0
	v_rcp_f32_e32 v86, v85
	s_nop 0
	v_fma_f32 v87, -v85, v86, 1.0
	v_fmac_f32_e32 v86, v87, v86
	v_div_scale_f32 v87, vcc, 1.0, v84, 1.0
	v_mul_f32_e32 v88, v87, v86
	v_fma_f32 v89, -v85, v88, v87
	v_fmac_f32_e32 v88, v89, v86
	v_fma_f32 v85, -v85, v88, v87
	v_div_fmas_f32 v85, v85, v86, v88
	v_div_fixup_f32 v84, v85, v84, 1.0
	v_pk_mul_f32 v[78:79], v[78:79], v[84:85] op_sel_hi:[1,0]
	v_pk_mul_f32 v[74:75], v[74:75], v[84:85] op_sel_hi:[1,0]
	v_pk_mul_f32 v[80:81], v[80:81], v[84:85] op_sel_hi:[1,0]
	v_pk_mul_f32 v[76:77], v[76:77], v[84:85] op_sel_hi:[1,0]
	v_max_f32_e32 v78, 0, v78
	v_max_f32_e32 v74, 0, v74
	v_max_f32_e32 v79, 0, v79
	v_max_f32_e32 v75, 0, v75
	v_pk_mul_f32 v[78:79], v[78:79], v[78:79]
	v_pk_mul_f32 v[86:87], v[74:75], v[74:75]
	v_max_f32_e32 v74, 0, v80
	v_max_f32_e32 v76, 0, v76
	v_max_f32_e32 v75, 0, v81
	v_max_f32_e32 v77, 0, v77
	v_pk_mul_f32 v[80:81], v[74:75], v[74:75]
	v_pk_mul_f32 v[88:89], v[76:77], v[76:77]
	v_cvt_pk_bf16_f32 v74, v78, v79
	v_lshl_add_u64 v[78:79], s[92:93], 0, v[82:83]
	v_pk_mul_f32 v[66:67], v[66:67], v[84:85] op_sel_hi:[1,0]
	v_cvt_pk_bf16_f32 v75, v80, v81
	v_cvt_pk_bf16_f32 v76, v86, v87
	v_cvt_pk_bf16_f32 v77, v88, v89
	v_lshl_add_u64 v[78:79], v[78:79], 0, v[122:123]
	v_pk_mul_f32 v[72:73], v[72:73], v[84:85] op_sel_hi:[1,0]
	v_pk_mul_f32 v[70:71], v[70:71], v[84:85] op_sel_hi:[1,0]
	v_pk_mul_f32 v[68:69], v[68:69], v[84:85] op_sel_hi:[1,0]
	v_max_f32_e32 v66, 0, v66
	v_max_f32_e32 v67, 0, v67
	global_store_dwordx4 v[78:79], v[74:77], off
	v_max_f32_e32 v70, 0, v70
	v_max_f32_e32 v71, 0, v71
	v_pk_mul_f32 v[74:75], v[66:67], v[66:67]
	v_max_f32_e32 v66, 0, v72
	v_max_f32_e32 v68, 0, v68
	v_max_f32_e32 v67, 0, v73
	v_max_f32_e32 v69, 0, v69
	v_pk_mul_f32 v[70:71], v[70:71], v[70:71]
	v_pk_mul_f32 v[72:73], v[66:67], v[66:67]
	v_pk_mul_f32 v[76:77], v[68:69], v[68:69]
	v_cvt_pk_bf16_f32 v66, v70, v71
	v_cvt_pk_bf16_f32 v67, v72, v73
	v_cvt_pk_bf16_f32 v68, v74, v75
	v_cvt_pk_bf16_f32 v69, v76, v77
	global_store_dwordx4 v[78:79], v[66:69], off offset:256
	s_nop 1
	v_add_u32_e32 v66, 0x80, v158
	v_ashrrev_i32_e32 v67, 31, v66
	v_lshlrev_b64 v[68:69], 7, v[66:67]
	v_lshl_add_u64 v[68:69], v[152:153], 0, v[68:69]
	global_load_dwordx4 v[70:73], v[68:69], off
	global_load_dwordx4 v[74:77], v[68:69], off offset:16
	v_lshlrev_b64 v[66:67], 14, v[66:67]
	s_waitcnt vmcnt(1)
	v_mov_b32_e32 v68, v70
	s_waitcnt vmcnt(0)
	v_mov_b32_e32 v69, v74
	v_mov_b32_e32 v74, v71
	v_mov_b32_e32 v70, v72
	v_mov_b32_e32 v71, v76
	v_mov_b32_e32 v76, v73
	v_pk_add_f32 v[68:69], v[68:69], v[74:75]
	v_pk_add_f32 v[70:71], v[70:71], v[76:77]
	s_nop 0
	v_pk_add_f32 v[68:69], v[68:69], v[70:71]
	s_nop 0
	v_add_f32_e32 v68, v68, v69
	v_mov_b32_e32 v69, v68
	s_nop 1
	v_permlane16_swap_b32_e32 v69, v68
	s_waitcnt lgkmcnt(0)
	v_add_f32_e32 v68, v68, v69
	v_mov_b32_e32 v69, v68
	s_nop 1
	v_permlane32_swap_b32_e32 v69, v68
	s_waitcnt lgkmcnt(0)
	v_add_f32_e32 v68, v68, v69
	v_fmamk_f32 v68, v68, 0x3a000000, v190
	v_cmp_gt_f32_e32 vcc, s72, v68
	v_mul_f32_e32 v69, 0x4f800000, v68
	s_nop 0
	v_cndmask_b32_e32 v68, v68, v69, vcc
	v_sqrt_f32_e32 v69, v68
	s_nop 0
	v_add_u32_e32 v70, -1, v69
	v_fma_f32 v71, -v70, v69, v68
	v_cmp_ge_f32_e64 s[0:1], 0, v71
	v_add_u32_e32 v71, 1, v69
	s_nop 0
	v_cndmask_b32_e64 v70, v69, v70, s[0:1]
	v_fma_f32 v69, -v71, v69, v68
	v_cmp_lt_f32_e64 s[0:1], 0, v69
	s_nop 1
	v_cndmask_b32_e64 v69, v70, v71, s[0:1]
	v_mul_f32_e32 v70, 0x37800000, v69
	v_cndmask_b32_e32 v69, v69, v70, vcc
	v_cmp_class_f32_e32 vcc, v68, v191
	s_nop 1
	v_cndmask_b32_e32 v68, v69, v68, vcc
	v_div_scale_f32 v69, s[0:1], v68, v68, 1.0
	v_rcp_f32_e32 v70, v69
	s_nop 0
	v_fma_f32 v71, -v69, v70, 1.0
	v_fmac_f32_e32 v70, v71, v70
	v_div_scale_f32 v71, vcc, 1.0, v68, 1.0
	v_mul_f32_e32 v72, v71, v70
	v_fma_f32 v73, -v69, v72, v71
	v_fmac_f32_e32 v72, v73, v70
	v_fma_f32 v69, -v69, v72, v71
	v_div_fmas_f32 v69, v69, v70, v72
	v_div_fixup_f32 v68, v69, v68, 1.0
	v_pk_mul_f32 v[62:63], v[62:63], v[68:69] op_sel_hi:[1,0]
	v_pk_mul_f32 v[58:59], v[58:59], v[68:69] op_sel_hi:[1,0]
	v_pk_mul_f32 v[64:65], v[64:65], v[68:69] op_sel_hi:[1,0]
	v_pk_mul_f32 v[60:61], v[60:61], v[68:69] op_sel_hi:[1,0]
	v_max_f32_e32 v62, 0, v62
	v_max_f32_e32 v58, 0, v58
	v_max_f32_e32 v63, 0, v63
	v_max_f32_e32 v59, 0, v59
	v_pk_mul_f32 v[62:63], v[62:63], v[62:63]
	v_pk_mul_f32 v[70:71], v[58:59], v[58:59]
	v_max_f32_e32 v58, 0, v64
; __device__ __forceinline__ unsigned cvt_pk_bf16(float lo, float hi) { const f32x2c_t v = {lo, hi}; const bf16x2c_t b = __builtin_convertvector(v, bf16x2c_t); return __builtin_bit_cast(unsigned, b); }
;     __device__ __forceinline__ void operator()(const f32x4 (&acc)[2][2][4][2], const Unit& u, int wr, int wc, int fr, int fq) const {
;     ...
;             for (int m = 0; m < 4; ++m) { const size_t row = (size_t)(row0 + ai * HALF + m * 16);
;                 const f32x4* sp = (const f32x4*)(SS + row * 32) + 2 * fq; float s;
;                 { const f32x4 t0 = sp[0], t1 = sp[1]; s = ((t0[0] + t0[1]) + (t0[2] + t0[3])) + ((t1[0] + t1[1]) + (t1[2] + t1[3])); }
;                 s += __shfl_xor(s, 16); s += __shfl_xor(s, 32);
;                 const float rstd = 1.0f / sqrtf(s * (1.0f / DM) + NORM_EPS);
; #pragma unroll
;                 for (int bj = 0; bj < 2; ++bj) { f32x4 v0 = acc[ai][bj][m][0] * rstd, v1 = acc[ai][bj][m][1] * rstd;
; #pragma unroll
;                     for (int e = 0; e < 4; ++e) { const float a = fmaxf(v0[e], 0.f), b = fmaxf(v1[e], 0.f); v0[e] = a * a; v1[e] = b * b; }
;                     u32x4 w; w.x = cvt_pk_bf16(v0[0], v0[1]); w.y = cvt_pk_bf16(v0[2], v0[3]); w.z = cvt_pk_bf16(v1[0], v1[1]); w.w = cvt_pk_bf16(v1[2], v1[3]);
;                     *(u32x4*)(H + row * DFF + col0 + bj * HALF) = w; } }
	v_max_f32_e32 v60, 0, v60
	v_max_f32_e32 v59, 0, v65
	v_max_f32_e32 v61, 0, v61
	v_pk_mul_f32 v[64:65], v[58:59], v[58:59]
	v_pk_mul_f32 v[72:73], v[60:61], v[60:61]
	v_cvt_pk_bf16_f32 v58, v62, v63
	v_lshl_add_u64 v[62:63], s[92:93], 0, v[66:67]
	v_pk_mul_f32 v[50:51], v[50:51], v[68:69] op_sel_hi:[1,0]
	v_cvt_pk_bf16_f32 v59, v64, v65
	v_cvt_pk_bf16_f32 v60, v70, v71
	v_cvt_pk_bf16_f32 v61, v72, v73
	v_lshl_add_u64 v[62:63], v[62:63], 0, v[122:123]
	v_pk_mul_f32 v[56:57], v[56:57], v[68:69] op_sel_hi:[1,0]
	v_pk_mul_f32 v[54:55], v[54:55], v[68:69] op_sel_hi:[1,0]
	v_pk_mul_f32 v[52:53], v[52:53], v[68:69] op_sel_hi:[1,0]
	v_max_f32_e32 v50, 0, v50
	v_max_f32_e32 v51, 0, v51
	global_store_dwordx4 v[62:63], v[58:61], off
	v_max_f32_e32 v54, 0, v54
	v_max_f32_e32 v55, 0, v55
	v_pk_mul_f32 v[58:59], v[50:51], v[50:51]
	v_max_f32_e32 v50, 0, v56
	v_max_f32_e32 v52, 0, v52
	v_max_f32_e32 v51, 0, v57
	v_max_f32_e32 v53, 0, v53
	v_pk_mul_f32 v[54:55], v[54:55], v[54:55]
	v_pk_mul_f32 v[56:57], v[50:51], v[50:51]
	v_pk_mul_f32 v[60:61], v[52:53], v[52:53]
	v_cvt_pk_bf16_f32 v50, v54, v55
	v_cvt_pk_bf16_f32 v51, v56, v57
	v_cvt_pk_bf16_f32 v52, v58, v59
	v_cvt_pk_bf16_f32 v53, v60, v61
	global_store_dwordx4 v[62:63], v[50:53], off offset:256
	s_nop 1
	v_add_u32_e32 v50, 0x90, v158
	v_ashrrev_i32_e32 v51, 31, v50
	v_lshlrev_b64 v[52:53], 7, v[50:51]
	v_lshl_add_u64 v[52:53], v[152:153], 0, v[52:53]
	global_load_dwordx4 v[54:57], v[52:53], off
	global_load_dwordx4 v[58:61], v[52:53], off offset:16
	v_lshlrev_b64 v[50:51], 14, v[50:51]
	s_waitcnt vmcnt(1)
	v_mov_b32_e32 v52, v54
	s_waitcnt vmcnt(0)
	v_mov_b32_e32 v53, v58
	v_mov_b32_e32 v58, v55
	v_mov_b32_e32 v54, v56
	v_mov_b32_e32 v55, v60
	v_mov_b32_e32 v60, v57
	v_pk_add_f32 v[52:53], v[52:53], v[58:59]
	v_pk_add_f32 v[54:55], v[54:55], v[60:61]
	s_nop 0
	v_pk_add_f32 v[52:53], v[52:53], v[54:55]
	s_nop 0
	v_add_f32_e32 v52, v52, v53
	v_mov_b32_e32 v53, v52
	s_nop 1
	v_permlane16_swap_b32_e32 v53, v52
	s_waitcnt lgkmcnt(0)
	v_add_f32_e32 v52, v52, v53
	v_mov_b32_e32 v53, v52
	s_nop 1
	v_permlane32_swap_b32_e32 v53, v52
	s_waitcnt lgkmcnt(0)
	v_add_f32_e32 v52, v52, v53
	v_fmamk_f32 v52, v52, 0x3a000000, v190
	v_cmp_gt_f32_e32 vcc, s72, v52
	v_mul_f32_e32 v53, 0x4f800000, v52
	s_nop 0
	v_cndmask_b32_e32 v52, v52, v53, vcc
	v_sqrt_f32_e32 v53, v52
	s_nop 0
	v_add_u32_e32 v54, -1, v53
	v_fma_f32 v55, -v54, v53, v52
	v_cmp_ge_f32_e64 s[0:1], 0, v55
	v_add_u32_e32 v55, 1, v53
	s_nop 0
	v_cndmask_b32_e64 v54, v53, v54, s[0:1]
	v_fma_f32 v53, -v55, v53, v52
	v_cmp_lt_f32_e64 s[0:1], 0, v53
	s_nop 1
	v_cndmask_b32_e64 v53, v54, v55, s[0:1]
	v_mul_f32_e32 v54, 0x37800000, v53
	v_cndmask_b32_e32 v53, v53, v54, vcc
	v_cmp_class_f32_e32 vcc, v52, v191
	s_nop 1
	v_cndmask_b32_e32 v52, v53, v52, vcc
	v_div_scale_f32 v53, s[0:1], v52, v52, 1.0
	v_rcp_f32_e32 v54, v53
	s_nop 0
	v_fma_f32 v55, -v53, v54, 1.0
	v_fmac_f32_e32 v54, v55, v54
	v_div_scale_f32 v55, vcc, 1.0, v52, 1.0
	v_mul_f32_e32 v56, v55, v54
	v_fma_f32 v57, -v53, v56, v55
	v_fmac_f32_e32 v56, v57, v54
	v_fma_f32 v53, -v53, v56, v55
	v_div_fmas_f32 v53, v53, v54, v56
	v_div_fixup_f32 v52, v53, v52, 1.0
	v_pk_mul_f32 v[46:47], v[46:47], v[52:53] op_sel_hi:[1,0]
	v_pk_mul_f32 v[42:43], v[42:43], v[52:53] op_sel_hi:[1,0]
	v_pk_mul_f32 v[48:49], v[48:49], v[52:53] op_sel_hi:[1,0]
	v_pk_mul_f32 v[44:45], v[44:45], v[52:53] op_sel_hi:[1,0]
	v_max_f32_e32 v46, 0, v46
	v_max_f32_e32 v42, 0, v42
	v_max_f32_e32 v47, 0, v47
	v_max_f32_e32 v43, 0, v43
	v_pk_mul_f32 v[46:47], v[46:47], v[46:47]
	v_pk_mul_f32 v[54:55], v[42:43], v[42:43]
	v_max_f32_e32 v42, 0, v48
	v_max_f32_e32 v44, 0, v44
	v_max_f32_e32 v43, 0, v49
	v_max_f32_e32 v45, 0, v45
	v_pk_mul_f32 v[48:49], v[42:43], v[42:43]
	v_pk_mul_f32 v[56:57], v[44:45], v[44:45]
	v_cvt_pk_bf16_f32 v42, v46, v47
	v_lshl_add_u64 v[46:47], s[92:93], 0, v[50:51]
	v_pk_mul_f32 v[34:35], v[34:35], v[52:53] op_sel_hi:[1,0]
	v_cvt_pk_bf16_f32 v43, v48, v49
	v_cvt_pk_bf16_f32 v44, v54, v55
	v_cvt_pk_bf16_f32 v45, v56, v57
	v_lshl_add_u64 v[46:47], v[46:47], 0, v[122:123]
	v_pk_mul_f32 v[40:41], v[40:41], v[52:53] op_sel_hi:[1,0]
	v_pk_mul_f32 v[38:39], v[38:39], v[52:53] op_sel_hi:[1,0]
	v_pk_mul_f32 v[36:37], v[36:37], v[52:53] op_sel_hi:[1,0]
	v_max_f32_e32 v34, 0, v34
	v_max_f32_e32 v35, 0, v35
	global_store_dwordx4 v[46:47], v[42:45], off
	v_max_f32_e32 v38, 0, v38
	v_max_f32_e32 v39, 0, v39
	v_pk_mul_f32 v[42:43], v[34:35], v[34:35]
	v_max_f32_e32 v34, 0, v40
	v_max_f32_e32 v36, 0, v36
	v_max_f32_e32 v35, 0, v41
	v_max_f32_e32 v37, 0, v37
	v_pk_mul_f32 v[38:39], v[38:39], v[38:39]
	v_pk_mul_f32 v[40:41], v[34:35], v[34:35]
	v_pk_mul_f32 v[44:45], v[36:37], v[36:37]
	v_cvt_pk_bf16_f32 v34, v38, v39
	v_cvt_pk_bf16_f32 v35, v40, v41
	v_cvt_pk_bf16_f32 v36, v42, v43
	v_cvt_pk_bf16_f32 v37, v44, v45
	global_store_dwordx4 v[46:47], v[34:37], off offset:256
	s_nop 1
	v_add_u32_e32 v34, 0xa0, v158
	v_ashrrev_i32_e32 v35, 31, v34
	v_lshlrev_b64 v[36:37], 7, v[34:35]
	v_lshl_add_u64 v[36:37], v[152:153], 0, v[36:37]
	global_load_dwordx4 v[38:41], v[36:37], off
	global_load_dwordx4 v[42:45], v[36:37], off offset:16
	v_lshlrev_b64 v[34:35], 14, v[34:35]
	s_waitcnt vmcnt(1)
	v_mov_b32_e32 v36, v38
	s_waitcnt vmcnt(0)
	v_mov_b32_e32 v37, v42
	v_mov_b32_e32 v42, v39
	v_mov_b32_e32 v38, v40
	v_mov_b32_e32 v39, v44
	v_mov_b32_e32 v44, v41
	v_pk_add_f32 v[36:37], v[36:37], v[42:43]
	v_pk_add_f32 v[38:39], v[38:39], v[44:45]
	s_nop 0
	v_pk_add_f32 v[36:37], v[36:37], v[38:39]
	s_nop 0
	v_add_f32_e32 v36, v36, v37
	v_mov_b32_e32 v37, v36
	s_nop 1
	v_permlane16_swap_b32_e32 v37, v36
	s_waitcnt lgkmcnt(0)
; __device__ __forceinline__ unsigned cvt_pk_bf16(float lo, float hi) { const f32x2c_t v = {lo, hi}; const bf16x2c_t b = __builtin_convertvector(v, bf16x2c_t); return __builtin_bit_cast(unsigned, b); }
;     __device__ __forceinline__ void operator()(const f32x4 (&acc)[2][2][4][2], const Unit& u, int wr, int wc, int fr, int fq) const {
;     ...
;             for (int m = 0; m < 4; ++m) { const size_t row = (size_t)(row0 + ai * HALF + m * 16);
;                 const f32x4* sp = (const f32x4*)(SS + row * 32) + 2 * fq; float s;
;                 { const f32x4 t0 = sp[0], t1 = sp[1]; s = ((t0[0] + t0[1]) + (t0[2] + t0[3])) + ((t1[0] + t1[1]) + (t1[2] + t1[3])); }
;                 s += __shfl_xor(s, 16); s += __shfl_xor(s, 32);
;                 const float rstd = 1.0f / sqrtf(s * (1.0f / DM) + NORM_EPS);
; #pragma unroll
;                 for (int bj = 0; bj < 2; ++bj) { f32x4 v0 = acc[ai][bj][m][0] * rstd, v1 = acc[ai][bj][m][1] * rstd;
; #pragma unroll
;                     for (int e = 0; e < 4; ++e) { const float a = fmaxf(v0[e], 0.f), b = fmaxf(v1[e], 0.f); v0[e] = a * a; v1[e] = b * b; }
;                     u32x4 w; w.x = cvt_pk_bf16(v0[0], v0[1]); w.y = cvt_pk_bf16(v0[2], v0[3]); w.z = cvt_pk_bf16(v1[0], v1[1]); w.w = cvt_pk_bf16(v1[2], v1[3]);
;                     *(u32x4*)(H + row * DFF + col0 + bj * HALF) = w; } }
	v_add_f32_e32 v36, v36, v37
	v_mov_b32_e32 v37, v36
	s_nop 1
	v_permlane32_swap_b32_e32 v37, v36
	s_waitcnt lgkmcnt(0)
	v_add_f32_e32 v36, v36, v37
	v_fmamk_f32 v36, v36, 0x3a000000, v190
	v_cmp_gt_f32_e32 vcc, s72, v36
	v_mul_f32_e32 v37, 0x4f800000, v36
	s_nop 0
	v_cndmask_b32_e32 v36, v36, v37, vcc
	v_sqrt_f32_e32 v37, v36
	s_nop 0
	v_add_u32_e32 v38, -1, v37
	v_fma_f32 v39, -v38, v37, v36
	v_cmp_ge_f32_e64 s[0:1], 0, v39
	v_add_u32_e32 v39, 1, v37
	s_nop 0
	v_cndmask_b32_e64 v38, v37, v38, s[0:1]
	v_fma_f32 v37, -v39, v37, v36
	v_cmp_lt_f32_e64 s[0:1], 0, v37
	s_nop 1
	v_cndmask_b32_e64 v37, v38, v39, s[0:1]
	v_mul_f32_e32 v38, 0x37800000, v37
	v_cndmask_b32_e32 v37, v37, v38, vcc
	v_cmp_class_f32_e32 vcc, v36, v191
	s_nop 1
	v_cndmask_b32_e32 v36, v37, v36, vcc
	v_div_scale_f32 v37, s[0:1], v36, v36, 1.0
	v_rcp_f32_e32 v38, v37
	s_nop 0
	v_fma_f32 v39, -v37, v38, 1.0
	v_fmac_f32_e32 v38, v39, v38
	v_div_scale_f32 v39, vcc, 1.0, v36, 1.0
	v_mul_f32_e32 v40, v39, v38
	v_fma_f32 v41, -v37, v40, v39
	v_fmac_f32_e32 v40, v41, v38
	v_fma_f32 v37, -v37, v40, v39
	v_div_fmas_f32 v37, v37, v38, v40
	v_div_fixup_f32 v36, v37, v36, 1.0
	v_pk_mul_f32 v[30:31], v[30:31], v[36:37] op_sel_hi:[1,0]
	v_pk_mul_f32 v[26:27], v[26:27], v[36:37] op_sel_hi:[1,0]
	v_pk_mul_f32 v[32:33], v[32:33], v[36:37] op_sel_hi:[1,0]
	v_pk_mul_f32 v[28:29], v[28:29], v[36:37] op_sel_hi:[1,0]
	v_max_f32_e32 v30, 0, v30
	v_max_f32_e32 v26, 0, v26
	v_max_f32_e32 v31, 0, v31
	v_max_f32_e32 v27, 0, v27
	v_pk_mul_f32 v[30:31], v[30:31], v[30:31]
	v_pk_mul_f32 v[38:39], v[26:27], v[26:27]
	v_max_f32_e32 v26, 0, v32
	v_max_f32_e32 v28, 0, v28
	v_max_f32_e32 v27, 0, v33
	v_max_f32_e32 v29, 0, v29
	v_pk_mul_f32 v[32:33], v[26:27], v[26:27]
	v_pk_mul_f32 v[40:41], v[28:29], v[28:29]
	v_cvt_pk_bf16_f32 v26, v30, v31
	v_lshl_add_u64 v[30:31], s[92:93], 0, v[34:35]
	v_pk_mul_f32 v[18:19], v[18:19], v[36:37] op_sel_hi:[1,0]
	v_cvt_pk_bf16_f32 v27, v32, v33
	v_cvt_pk_bf16_f32 v28, v38, v39
	v_cvt_pk_bf16_f32 v29, v40, v41
	v_lshl_add_u64 v[30:31], v[30:31], 0, v[122:123]
	v_pk_mul_f32 v[24:25], v[24:25], v[36:37] op_sel_hi:[1,0]
	v_pk_mul_f32 v[22:23], v[22:23], v[36:37] op_sel_hi:[1,0]
	v_pk_mul_f32 v[20:21], v[20:21], v[36:37] op_sel_hi:[1,0]
	v_max_f32_e32 v18, 0, v18
	v_max_f32_e32 v19, 0, v19
	global_store_dwordx4 v[30:31], v[26:29], off
	v_max_f32_e32 v22, 0, v22
	v_max_f32_e32 v23, 0, v23
	v_pk_mul_f32 v[26:27], v[18:19], v[18:19]
	v_max_f32_e32 v18, 0, v24
	v_max_f32_e32 v20, 0, v20
	v_max_f32_e32 v19, 0, v25
	v_max_f32_e32 v21, 0, v21
	v_pk_mul_f32 v[22:23], v[22:23], v[22:23]
	v_pk_mul_f32 v[24:25], v[18:19], v[18:19]
	v_pk_mul_f32 v[28:29], v[20:21], v[20:21]
	v_cvt_pk_bf16_f32 v18, v22, v23
	v_cvt_pk_bf16_f32 v19, v24, v25
	v_cvt_pk_bf16_f32 v20, v26, v27
	v_cvt_pk_bf16_f32 v21, v28, v29
	global_store_dwordx4 v[30:31], v[18:21], off offset:256
	s_nop 1
	v_add_u32_e32 v18, 0xb0, v158
	v_ashrrev_i32_e32 v19, 31, v18
	v_lshlrev_b64 v[20:21], 7, v[18:19]
	v_lshl_add_u64 v[20:21], v[152:153], 0, v[20:21]
	global_load_dwordx4 v[22:25], v[20:21], off
	global_load_dwordx4 v[26:29], v[20:21], off offset:16
	v_lshlrev_b64 v[18:19], 14, v[18:19]
	s_waitcnt vmcnt(1)
	v_mov_b32_e32 v20, v22
	s_waitcnt vmcnt(0)
	v_mov_b32_e32 v21, v26
	v_mov_b32_e32 v26, v23
	v_mov_b32_e32 v22, v24
	v_mov_b32_e32 v23, v28
	v_mov_b32_e32 v28, v25
	v_pk_add_f32 v[20:21], v[20:21], v[26:27]
	v_pk_add_f32 v[22:23], v[22:23], v[28:29]
	s_nop 0
	v_pk_add_f32 v[20:21], v[20:21], v[22:23]
	s_nop 0
	v_add_f32_e32 v20, v20, v21
	v_mov_b32_e32 v21, v20
	s_nop 1
	v_permlane16_swap_b32_e32 v21, v20
	s_waitcnt lgkmcnt(0)
	v_add_f32_e32 v20, v20, v21
	v_mov_b32_e32 v21, v20
	s_nop 1
	v_permlane32_swap_b32_e32 v21, v20
	s_waitcnt lgkmcnt(0)
	v_add_f32_e32 v20, v20, v21
	v_fmamk_f32 v20, v20, 0x3a000000, v190
	v_cmp_gt_f32_e32 vcc, s72, v20
	v_mul_f32_e32 v21, 0x4f800000, v20
	s_nop 0
	v_cndmask_b32_e32 v20, v20, v21, vcc
	v_sqrt_f32_e32 v21, v20
	s_nop 0
	v_add_u32_e32 v22, -1, v21
	v_fma_f32 v23, -v22, v21, v20
	v_cmp_ge_f32_e64 s[0:1], 0, v23
	v_add_u32_e32 v23, 1, v21
	s_nop 0
	v_cndmask_b32_e64 v22, v21, v22, s[0:1]
	v_fma_f32 v21, -v23, v21, v20
	v_cmp_lt_f32_e64 s[0:1], 0, v21
	s_nop 1
	v_cndmask_b32_e64 v21, v22, v23, s[0:1]
	v_mul_f32_e32 v22, 0x37800000, v21
	v_cndmask_b32_e32 v21, v21, v22, vcc
	v_cmp_class_f32_e32 vcc, v20, v191
	s_nop 1
	v_cndmask_b32_e32 v20, v21, v20, vcc
	v_div_scale_f32 v21, s[0:1], v20, v20, 1.0
	v_rcp_f32_e32 v22, v21
	s_mov_b64 s[0:1], -1
	v_fma_f32 v23, -v21, v22, 1.0
	v_fmac_f32_e32 v22, v23, v22
	v_div_scale_f32 v23, vcc, 1.0, v20, 1.0
	v_mul_f32_e32 v24, v23, v22
	v_fma_f32 v25, -v21, v24, v23
	v_fmac_f32_e32 v24, v25, v22
	v_fma_f32 v21, -v21, v24, v23
	v_div_fmas_f32 v21, v21, v22, v24
	v_div_fixup_f32 v20, v21, v20, 1.0
	v_pk_mul_f32 v[14:15], v[14:15], v[20:21] op_sel_hi:[1,0]
	v_pk_mul_f32 v[10:11], v[10:11], v[20:21] op_sel_hi:[1,0]
	v_pk_mul_f32 v[16:17], v[16:17], v[20:21] op_sel_hi:[1,0]
	v_pk_mul_f32 v[12:13], v[12:13], v[20:21] op_sel_hi:[1,0]
	v_max_f32_e32 v14, 0, v14
	v_max_f32_e32 v10, 0, v10
	v_max_f32_e32 v15, 0, v15
	v_max_f32_e32 v11, 0, v11
	v_pk_mul_f32 v[14:15], v[14:15], v[14:15]
	v_pk_mul_f32 v[22:23], v[10:11], v[10:11]
	v_max_f32_e32 v10, 0, v16
	v_max_f32_e32 v12, 0, v12
	v_max_f32_e32 v11, 0, v17
	v_max_f32_e32 v13, 0, v13
	v_pk_mul_f32 v[16:17], v[10:11], v[10:11]
	v_pk_mul_f32 v[24:25], v[12:13], v[12:13]
	v_cvt_pk_bf16_f32 v10, v14, v15
	v_lshl_add_u64 v[14:15], s[92:93], 0, v[18:19]
	v_pk_mul_f32 v[2:3], v[2:3], v[20:21] op_sel_hi:[1,0]
	v_cvt_pk_bf16_f32 v11, v16, v17
	v_cvt_pk_bf16_f32 v12, v22, v23
	v_cvt_pk_bf16_f32 v13, v24, v25
	v_lshl_add_u64 v[14:15], v[14:15], 0, v[122:123]
	v_pk_mul_f32 v[8:9], v[8:9], v[20:21] op_sel_hi:[1,0]
	v_pk_mul_f32 v[6:7], v[6:7], v[20:21] op_sel_hi:[1,0]
	v_pk_mul_f32 v[4:5], v[4:5], v[20:21] op_sel_hi:[1,0]
	v_max_f32_e32 v2, 0, v2
	v_max_f32_e32 v3, 0, v3
	global_store_dwordx4 v[14:15], v[10:13], off
	v_max_f32_e32 v6, 0, v6
	v_max_f32_e32 v7, 0, v7
	v_pk_mul_f32 v[10:11], v[2:3], v[2:3]
	v_max_f32_e32 v2, 0, v8
	v_max_f32_e32 v4, 0, v4
	v_max_f32_e32 v3, 0, v9
	v_max_f32_e32 v5, 0, v5
	v_pk_mul_f32 v[6:7], v[6:7], v[6:7]
	v_pk_mul_f32 v[8:9], v[2:3], v[2:3]
	v_pk_mul_f32 v[12:13], v[4:5], v[4:5]
	v_cvt_pk_bf16_f32 v2, v6, v7
	v_cvt_pk_bf16_f32 v3, v8, v9
	v_cvt_pk_bf16_f32 v4, v10, v11
	v_cvt_pk_bf16_f32 v5, v12, v13
	s_andn2_b64 vcc, exec, s[40:41]
	global_store_dwordx4 v[14:15], v[2:5], off offset:256
	s_cbranch_vccnz .LBB0_68
	s_andn2_b64 vcc, exec, s[12:13]
	s_cbranch_vccnz .LBB0_67
	s_barrier
	s_branch .LBB0_67
